# v80 + nt on the P5 epilogue's gate loads (second gate half, read once)
# baseline (speedup 1.0000x reference)
; __device__ __forceinline__ float bf_lo(unsigned w) { return __uint_as_float(w << 16); }
; __device__ __forceinline__ float bf_hi(unsigned w) { return __uint_as_float(w & 0xffff0000u); }
; #define PG8_PACK8(v0, v1) ((u32x4){cvt_pk_bf16((v0)[0], (v0)[1]), cvt_pk_bf16((v0)[2], (v0)[3]), cvt_pk_bf16((v1)[0], (v1)[1]), cvt_pk_bf16((v1)[2], (v1)[3])})
;     __device__ __forceinline__ void operator()(const f32x4 (&acc)[2][2][4][2], const Unit& u, int wr, int wc, int fr, int fq) const {
;     ...
;           for (int mb = 0; mb < 4; mb += MB) { u32x4 gq[MB][2], oq[MB][2];
; #pragma unroll
;             for (int m = 0; m < MB; ++m)
; #pragma unroll
;                 for (int bj = 0; bj < 2; ++bj) { const size_t row = (size_t)(row0 + ai * HALF + (mb + m) * 16); const int col = col0 + bj * HALF;
;                     gq[m][bj] = *(const u32x4*)(gate + row * 4096 + goff + col); if (SECOND) oq[m][bj] = *(const u32x4*)(merged + row * 2048 + col); }
;             asm volatile("" ::: "memory");
; #pragma unroll
;             for (int m = 0; m < MB; ++m)
; #pragma unroll
;                 for (int bj = 0; bj < 2; ++bj) { const size_t row = (size_t)(row0 + ai * HALF + (mb + m) * 16); const int col = col0 + bj * HALF; const u32x4 g = gq[m][bj];
;                     f32x4 v0 = acc[ai][bj][mb + m][0], v1 = acc[ai][bj][mb + m][1];
;                     v0[0] *= bf_lo(g.x); v0[1] *= bf_hi(g.x); v0[2] *= bf_lo(g.y); v0[3] *= bf_hi(g.y);
;                     v1[0] *= bf_lo(g.z); v1[1] *= bf_hi(g.z); v1[2] *= bf_lo(g.w); v1[3] *= bf_hi(g.w);
;                     if (SECOND) { const u32x4 o = oq[m][bj];
;                         v0[0] += bf_lo(o.x); v0[1] += bf_hi(o.x); v0[2] += bf_lo(o.y); v0[3] += bf_hi(o.y);
;                         v1[0] += bf_lo(o.z); v1[1] += bf_hi(o.z); v1[2] += bf_lo(o.w); v1[3] += bf_hi(o.w); }
;                     *(u32x4*)(merged + row * 2048 + col) = PG8_PACK8(v0, v1); }
.LBB0_761:
	v_lshl_add_u32 v156, s55, 8, v162
	v_lshl_or_b32 v130, s54, 8, v164
	v_ashrrev_i32_e32 v157, 31, v156
	v_ashrrev_i32_e32 v131, 31, v130
	v_lshlrev_b64 v[132:133], 13, v[156:157]
	v_lshl_add_u64 v[132:133], s[16:17], 0, v[132:133]
	v_lshlrev_b64 v[158:159], 1, v[130:131]
	v_lshlrev_b64 v[134:135], 12, v[156:157]
	v_lshl_add_u64 v[130:131], v[132:133], 0, v[158:159]
	v_lshl_add_u64 v[134:135], s[10:11], 0, v[134:135]
	global_load_dwordx4 v[166:169], v[130:131], off nt
	v_lshl_add_u64 v[182:183], v[134:135], 0, v[158:159]
	global_load_dwordx4 v[170:173], v[182:183], off
	global_load_dwordx4 v[174:177], v[130:131], off offset:256 nt
	global_load_dwordx4 v[178:181], v[182:183], off offset:256
	v_or_b32_e32 v130, 16, v156
	v_ashrrev_i32_e32 v131, 31, v130
	v_lshlrev_b64 v[132:133], 13, v[130:131]
	v_lshl_add_u64 v[132:133], s[16:17], 0, v[132:133]
	v_lshlrev_b64 v[130:131], 12, v[130:131]
	v_lshl_add_u64 v[132:133], v[132:133], 0, v[158:159]
	v_lshl_add_u64 v[130:131], s[10:11], 0, v[130:131]
	global_load_dwordx4 v[142:145], v[132:133], off nt
	v_lshl_add_u64 v[160:161], v[130:131], 0, v[158:159]
	global_load_dwordx4 v[138:141], v[160:161], off
	global_load_dwordx4 v[134:137], v[132:133], off offset:256 nt
	s_nop 0
	global_load_dwordx4 v[130:133], v[160:161], off offset:256
	s_mov_b64 s[26:27], -1
	s_andn2_b64 vcc, exec, s[6:7]
	s_waitcnt vmcnt(0)
	v_lshlrev_b32_e32 v186, 16, v170
	v_lshlrev_b32_e32 v184, 16, v166
	v_and_b32_e32 v185, 0xffff0000, v166
	v_and_b32_e32 v187, 0xffff0000, v170
	v_lshlrev_b32_e32 v166, 16, v167
	v_and_b32_e32 v167, 0xffff0000, v167
	v_lshlrev_b32_e32 v170, 16, v171
	v_and_b32_e32 v171, 0xffff0000, v171
	v_pk_fma_f32 v[128:129], v[128:129], v[166:167], v[170:171]
	v_lshlrev_b32_e32 v166, 16, v168
	v_and_b32_e32 v167, 0xffff0000, v168
	v_lshlrev_b32_e32 v170, 16, v172
	v_and_b32_e32 v171, 0xffff0000, v172
	v_pk_fma_f32 v[166:167], v[122:123], v[166:167], v[170:171]
	v_lshlrev_b32_e32 v122, 16, v169
	v_and_b32_e32 v123, 0xffff0000, v169
	v_lshlrev_b32_e32 v168, 16, v173
	v_and_b32_e32 v169, 0xffff0000, v173
	v_pk_fma_f32 v[126:127], v[126:127], v[184:185], v[186:187]
	v_pk_fma_f32 v[168:169], v[124:125], v[122:123], v[168:169]
	v_cvt_pk_bf16_f32 v122, v126, v127
	v_cvt_pk_bf16_f32 v123, v128, v129
	v_cvt_pk_bf16_f32 v124, v166, v167
	v_cvt_pk_bf16_f32 v125, v168, v169
	global_store_dwordx4 v[182:183], v[122:125], off
	s_nop 1
	v_lshlrev_b32_e32 v122, 16, v174
	v_and_b32_e32 v123, 0xffff0000, v174
	v_lshlrev_b32_e32 v124, 16, v178
	v_and_b32_e32 v125, 0xffff0000, v178
	v_pk_fma_f32 v[118:119], v[118:119], v[122:123], v[124:125]
	v_lshlrev_b32_e32 v122, 16, v175
	v_and_b32_e32 v123, 0xffff0000, v175
	v_lshlrev_b32_e32 v124, 16, v179
	v_and_b32_e32 v125, 0xffff0000, v179
	v_pk_fma_f32 v[120:121], v[120:121], v[122:123], v[124:125]
	v_lshlrev_b32_e32 v122, 16, v176
	v_and_b32_e32 v123, 0xffff0000, v176
	v_lshlrev_b32_e32 v124, 16, v180
	v_and_b32_e32 v125, 0xffff0000, v180
	v_pk_fma_f32 v[122:123], v[114:115], v[122:123], v[124:125]
	v_lshlrev_b32_e32 v114, 16, v177
	v_and_b32_e32 v115, 0xffff0000, v177
	v_lshlrev_b32_e32 v124, 16, v181
	v_and_b32_e32 v125, 0xffff0000, v181
	v_pk_fma_f32 v[124:125], v[116:117], v[114:115], v[124:125]
	v_cvt_pk_bf16_f32 v114, v118, v119
	v_cvt_pk_bf16_f32 v115, v120, v121
	v_cvt_pk_bf16_f32 v116, v122, v123
	v_cvt_pk_bf16_f32 v117, v124, v125
	global_store_dwordx4 v[182:183], v[114:117], off offset:256
	s_nop 1
	v_lshlrev_b32_e32 v114, 16, v142
	v_and_b32_e32 v115, 0xffff0000, v142
	v_lshlrev_b32_e32 v116, 16, v138
	v_and_b32_e32 v117, 0xffff0000, v138
	v_pk_fma_f32 v[110:111], v[110:111], v[114:115], v[116:117]
	v_lshlrev_b32_e32 v114, 16, v143
	v_and_b32_e32 v115, 0xffff0000, v143
	v_lshlrev_b32_e32 v116, 16, v139
	v_and_b32_e32 v117, 0xffff0000, v139
	v_pk_fma_f32 v[112:113], v[112:113], v[114:115], v[116:117]
	v_lshlrev_b32_e32 v114, 16, v144
	v_and_b32_e32 v115, 0xffff0000, v144
	v_lshlrev_b32_e32 v116, 16, v140
	v_and_b32_e32 v117, 0xffff0000, v140
	v_pk_fma_f32 v[114:115], v[106:107], v[114:115], v[116:117]
	v_lshlrev_b32_e32 v106, 16, v145
	v_and_b32_e32 v107, 0xffff0000, v145
	v_lshlrev_b32_e32 v116, 16, v141
	v_and_b32_e32 v117, 0xffff0000, v141
	v_pk_fma_f32 v[116:117], v[108:109], v[106:107], v[116:117]
	v_cvt_pk_bf16_f32 v106, v110, v111
	v_cvt_pk_bf16_f32 v107, v112, v113
	v_cvt_pk_bf16_f32 v108, v114, v115
	v_cvt_pk_bf16_f32 v109, v116, v117
	global_store_dwordx4 v[160:161], v[106:109], off
	v_or_b32_e32 v114, 48, v156
	v_ashrrev_i32_e32 v115, 31, v114
	v_lshlrev_b32_e32 v106, 16, v134
	v_and_b32_e32 v107, 0xffff0000, v134
	v_lshlrev_b32_e32 v108, 16, v130
	v_and_b32_e32 v109, 0xffff0000, v130
	v_pk_fma_f32 v[102:103], v[102:103], v[106:107], v[108:109]
	v_lshlrev_b32_e32 v106, 16, v135
	v_and_b32_e32 v107, 0xffff0000, v135
	v_lshlrev_b32_e32 v108, 16, v131
	v_and_b32_e32 v109, 0xffff0000, v131
	v_pk_fma_f32 v[104:105], v[104:105], v[106:107], v[108:109]
	v_lshlrev_b32_e32 v106, 16, v136
	v_and_b32_e32 v107, 0xffff0000, v136
	v_lshlrev_b32_e32 v108, 16, v132
	v_and_b32_e32 v109, 0xffff0000, v132
	v_pk_fma_f32 v[106:107], v[98:99], v[106:107], v[108:109]
	v_lshlrev_b32_e32 v98, 16, v137
	v_and_b32_e32 v99, 0xffff0000, v137
	v_lshlrev_b32_e32 v108, 16, v133
	v_and_b32_e32 v109, 0xffff0000, v133
	v_pk_fma_f32 v[108:109], v[100:101], v[98:99], v[108:109]
	v_cvt_pk_bf16_f32 v98, v102, v103
	v_cvt_pk_bf16_f32 v99, v104, v105
	v_cvt_pk_bf16_f32 v100, v106, v107
	v_cvt_pk_bf16_f32 v101, v108, v109
	global_store_dwordx4 v[160:161], v[98:101], off offset:256
	v_lshlrev_b64 v[116:117], 13, v[114:115]
	v_lshl_add_u64 v[116:117], s[16:17], 0, v[116:117]
	v_or_b32_e32 v98, 32, v156
	v_ashrrev_i32_e32 v99, 31, v98
	v_lshlrev_b64 v[100:101], 13, v[98:99]
	v_lshl_add_u64 v[100:101], s[16:17], 0, v[100:101]
	v_lshlrev_b64 v[98:99], 12, v[98:99]
	v_lshl_add_u64 v[106:107], v[100:101], 0, v[158:159]
	v_lshl_add_u64 v[102:103], s[10:11], 0, v[98:99]
	global_load_dwordx4 v[98:101], v[106:107], off nt
	v_lshl_add_u64 v[130:131], v[102:103], 0, v[158:159]
	global_load_dwordx4 v[102:105], v[130:131], off
	s_nop 0
	global_load_dwordx4 v[106:109], v[106:107], off offset:256 nt
	s_nop 0
	global_load_dwordx4 v[110:113], v[130:131], off offset:256
	v_lshlrev_b64 v[114:115], 12, v[114:115]
	v_lshl_add_u64 v[122:123], v[116:117], 0, v[158:159]
	v_lshl_add_u64 v[118:119], s[10:11], 0, v[114:115]
	global_load_dwordx4 v[114:117], v[122:123], off nt
	v_lshl_add_u64 v[132:133], v[118:119], 0, v[158:159]
	global_load_dwordx4 v[118:121], v[132:133], off
	s_nop 0
	global_load_dwordx4 v[122:125], v[122:123], off offset:256 nt
	s_nop 0
	global_load_dwordx4 v[126:129], v[132:133], off offset:256
	s_waitcnt vmcnt(7)
; __device__ __forceinline__ float bf_lo(unsigned w) { return __uint_as_float(w << 16); }
; __device__ __forceinline__ float bf_hi(unsigned w) { return __uint_as_float(w & 0xffff0000u); }
; #define PG8_PACK8(v0, v1) ((u32x4){cvt_pk_bf16((v0)[0], (v0)[1]), cvt_pk_bf16((v0)[2], (v0)[3]), cvt_pk_bf16((v1)[0], (v1)[1]), cvt_pk_bf16((v1)[2], (v1)[3])})
;     __device__ __forceinline__ void operator()(const f32x4 (&acc)[2][2][4][2], const Unit& u, int wr, int wc, int fr, int fq) const {
;     ...
;           for (int mb = 0; mb < 4; mb += MB) { u32x4 gq[MB][2], oq[MB][2];
; #pragma unroll
;             for (int m = 0; m < MB; ++m)
; #pragma unroll
;                 for (int bj = 0; bj < 2; ++bj) { const size_t row = (size_t)(row0 + ai * HALF + (mb + m) * 16); const int col = col0 + bj * HALF;
;                     gq[m][bj] = *(const u32x4*)(gate + row * 4096 + goff + col); if (SECOND) oq[m][bj] = *(const u32x4*)(merged + row * 2048 + col); }
;             asm volatile("" ::: "memory");
; #pragma unroll
;             for (int m = 0; m < MB; ++m)
; #pragma unroll
;                 for (int bj = 0; bj < 2; ++bj) { const size_t row = (size_t)(row0 + ai * HALF + (mb + m) * 16); const int col = col0 + bj * HALF; const u32x4 g = gq[m][bj];
;                     f32x4 v0 = acc[ai][bj][mb + m][0], v1 = acc[ai][bj][mb + m][1];
;                     v0[0] *= bf_lo(g.x); v0[1] *= bf_hi(g.x); v0[2] *= bf_lo(g.y); v0[3] *= bf_hi(g.y);
;                     v1[0] *= bf_lo(g.z); v1[1] *= bf_hi(g.z); v1[2] *= bf_lo(g.w); v1[3] *= bf_hi(g.w);
;                     if (SECOND) { const u32x4 o = oq[m][bj];
;                         v0[0] += bf_lo(o.x); v0[1] += bf_hi(o.x); v0[2] += bf_lo(o.y); v0[3] += bf_hi(o.y);
;                         v1[0] += bf_lo(o.z); v1[1] += bf_hi(o.z); v1[2] += bf_lo(o.w); v1[3] += bf_hi(o.w); }
;                     *(u32x4*)(merged + row * 2048 + col) = PG8_PACK8(v0, v1); }
	v_lshlrev_b32_e32 v134, 16, v98
	v_and_b32_e32 v135, 0xffff0000, v98
	s_waitcnt vmcnt(6)
	v_lshlrev_b32_e32 v136, 16, v102
	v_and_b32_e32 v137, 0xffff0000, v102
	v_lshlrev_b32_e32 v98, 16, v99
	v_and_b32_e32 v99, 0xffff0000, v99
	v_lshlrev_b32_e32 v102, 16, v103
	v_and_b32_e32 v103, 0xffff0000, v103
	v_pk_fma_f32 v[96:97], v[96:97], v[98:99], v[102:103]
	v_lshlrev_b32_e32 v98, 16, v100
	v_and_b32_e32 v99, 0xffff0000, v100
	v_lshlrev_b32_e32 v102, 16, v104
	v_and_b32_e32 v103, 0xffff0000, v104
	v_pk_fma_f32 v[98:99], v[90:91], v[98:99], v[102:103]
	v_lshlrev_b32_e32 v90, 16, v101
	v_and_b32_e32 v91, 0xffff0000, v101
	v_lshlrev_b32_e32 v100, 16, v105
	v_and_b32_e32 v101, 0xffff0000, v105
	v_pk_fma_f32 v[94:95], v[94:95], v[134:135], v[136:137]
	v_pk_fma_f32 v[100:101], v[92:93], v[90:91], v[100:101]
	v_cvt_pk_bf16_f32 v90, v94, v95
	v_cvt_pk_bf16_f32 v91, v96, v97
	v_cvt_pk_bf16_f32 v92, v98, v99
	v_cvt_pk_bf16_f32 v93, v100, v101
	global_store_dwordx4 v[130:131], v[90:93], off
	s_waitcnt vmcnt(6)
	s_nop 0
	v_lshlrev_b32_e32 v90, 16, v106
	v_and_b32_e32 v91, 0xffff0000, v106
	s_waitcnt vmcnt(5)
	v_lshlrev_b32_e32 v92, 16, v110
	v_and_b32_e32 v93, 0xffff0000, v110
	v_pk_fma_f32 v[86:87], v[86:87], v[90:91], v[92:93]
	v_lshlrev_b32_e32 v90, 16, v107
	v_and_b32_e32 v91, 0xffff0000, v107
	v_lshlrev_b32_e32 v92, 16, v111
	v_and_b32_e32 v93, 0xffff0000, v111
	v_pk_fma_f32 v[88:89], v[88:89], v[90:91], v[92:93]
	v_lshlrev_b32_e32 v90, 16, v108
	v_and_b32_e32 v91, 0xffff0000, v108
	v_lshlrev_b32_e32 v92, 16, v112
	v_and_b32_e32 v93, 0xffff0000, v112
	v_pk_fma_f32 v[90:91], v[82:83], v[90:91], v[92:93]
	v_lshlrev_b32_e32 v82, 16, v109
	v_and_b32_e32 v83, 0xffff0000, v109
	v_lshlrev_b32_e32 v92, 16, v113
	v_and_b32_e32 v93, 0xffff0000, v113
	v_pk_fma_f32 v[92:93], v[84:85], v[82:83], v[92:93]
	v_cvt_pk_bf16_f32 v82, v86, v87
	v_cvt_pk_bf16_f32 v83, v88, v89
	v_cvt_pk_bf16_f32 v84, v90, v91
	v_cvt_pk_bf16_f32 v85, v92, v93
	global_store_dwordx4 v[130:131], v[82:85], off offset:256
	s_waitcnt vmcnt(5)
	s_nop 0
	v_lshlrev_b32_e32 v82, 16, v114
	v_and_b32_e32 v83, 0xffff0000, v114
	s_waitcnt vmcnt(4)
	v_lshlrev_b32_e32 v84, 16, v118
	v_and_b32_e32 v85, 0xffff0000, v118
	v_pk_fma_f32 v[78:79], v[78:79], v[82:83], v[84:85]
	v_lshlrev_b32_e32 v82, 16, v115
	v_and_b32_e32 v83, 0xffff0000, v115
	v_lshlrev_b32_e32 v84, 16, v119
	v_and_b32_e32 v85, 0xffff0000, v119
	v_pk_fma_f32 v[80:81], v[80:81], v[82:83], v[84:85]
	v_lshlrev_b32_e32 v82, 16, v116
	v_and_b32_e32 v83, 0xffff0000, v116
	v_lshlrev_b32_e32 v84, 16, v120
	v_and_b32_e32 v85, 0xffff0000, v120
	v_pk_fma_f32 v[82:83], v[74:75], v[82:83], v[84:85]
	v_lshlrev_b32_e32 v74, 16, v117
	v_and_b32_e32 v75, 0xffff0000, v117
	v_lshlrev_b32_e32 v84, 16, v121
	v_and_b32_e32 v85, 0xffff0000, v121
	v_pk_fma_f32 v[84:85], v[76:77], v[74:75], v[84:85]
	v_cvt_pk_bf16_f32 v74, v78, v79
	v_cvt_pk_bf16_f32 v75, v80, v81
	v_cvt_pk_bf16_f32 v76, v82, v83
	v_cvt_pk_bf16_f32 v77, v84, v85
	global_store_dwordx4 v[132:133], v[74:77], off
	v_add_u32_e32 v82, 0x90, v156
	v_ashrrev_i32_e32 v83, 31, v82
	s_waitcnt vmcnt(4)
	v_lshlrev_b32_e32 v74, 16, v122
	v_and_b32_e32 v75, 0xffff0000, v122
	s_waitcnt vmcnt(3)
	v_lshlrev_b32_e32 v76, 16, v126
	v_and_b32_e32 v77, 0xffff0000, v126
	v_pk_fma_f32 v[70:71], v[70:71], v[74:75], v[76:77]
	v_lshlrev_b32_e32 v74, 16, v123
	v_and_b32_e32 v75, 0xffff0000, v123
	v_lshlrev_b32_e32 v76, 16, v127
	v_and_b32_e32 v77, 0xffff0000, v127
	v_pk_fma_f32 v[72:73], v[72:73], v[74:75], v[76:77]
	v_lshlrev_b32_e32 v74, 16, v124
	v_and_b32_e32 v75, 0xffff0000, v124
	v_lshlrev_b32_e32 v76, 16, v128
	v_and_b32_e32 v77, 0xffff0000, v128
	v_pk_fma_f32 v[74:75], v[66:67], v[74:75], v[76:77]
	v_lshlrev_b32_e32 v66, 16, v125
	v_and_b32_e32 v67, 0xffff0000, v125
	v_lshlrev_b32_e32 v76, 16, v129
	v_and_b32_e32 v77, 0xffff0000, v129
	v_pk_fma_f32 v[76:77], v[68:69], v[66:67], v[76:77]
	v_cvt_pk_bf16_f32 v66, v70, v71
	v_cvt_pk_bf16_f32 v67, v72, v73
	v_cvt_pk_bf16_f32 v68, v74, v75
	v_cvt_pk_bf16_f32 v69, v76, v77
	global_store_dwordx4 v[132:133], v[66:69], off offset:256
	v_lshlrev_b64 v[84:85], 13, v[82:83]
	v_lshl_add_u64 v[84:85], s[16:17], 0, v[84:85]
	v_add_u32_e32 v66, 0x80, v156
	v_ashrrev_i32_e32 v67, 31, v66
	v_lshlrev_b64 v[68:69], 13, v[66:67]
	v_lshl_add_u64 v[68:69], s[16:17], 0, v[68:69]
	v_lshlrev_b64 v[66:67], 12, v[66:67]
	v_lshl_add_u64 v[74:75], v[68:69], 0, v[158:159]
	v_lshl_add_u64 v[70:71], s[10:11], 0, v[66:67]
	global_load_dwordx4 v[66:69], v[74:75], off nt
	v_lshl_add_u64 v[98:99], v[70:71], 0, v[158:159]
	global_load_dwordx4 v[70:73], v[98:99], off
	s_nop 0
	global_load_dwordx4 v[74:77], v[74:75], off offset:256 nt
	s_nop 0
	global_load_dwordx4 v[78:81], v[98:99], off offset:256
	v_lshlrev_b64 v[82:83], 12, v[82:83]
	v_lshl_add_u64 v[90:91], v[84:85], 0, v[158:159]
	v_lshl_add_u64 v[86:87], s[10:11], 0, v[82:83]
	global_load_dwordx4 v[82:85], v[90:91], off nt
	v_lshl_add_u64 v[100:101], v[86:87], 0, v[158:159]
	global_load_dwordx4 v[86:89], v[100:101], off
	s_nop 0
	global_load_dwordx4 v[90:93], v[90:91], off offset:256 nt
	s_nop 0
	global_load_dwordx4 v[94:97], v[100:101], off offset:256
	s_waitcnt vmcnt(7)
	v_lshlrev_b32_e32 v102, 16, v66
	v_and_b32_e32 v103, 0xffff0000, v66
	s_waitcnt vmcnt(6)
; __device__ __forceinline__ float bf_lo(unsigned w) { return __uint_as_float(w << 16); }
; __device__ __forceinline__ float bf_hi(unsigned w) { return __uint_as_float(w & 0xffff0000u); }
; #define PG8_PACK8(v0, v1) ((u32x4){cvt_pk_bf16((v0)[0], (v0)[1]), cvt_pk_bf16((v0)[2], (v0)[3]), cvt_pk_bf16((v1)[0], (v1)[1]), cvt_pk_bf16((v1)[2], (v1)[3])})
;     __device__ __forceinline__ void operator()(const f32x4 (&acc)[2][2][4][2], const Unit& u, int wr, int wc, int fr, int fq) const {
;     ...
;           for (int mb = 0; mb < 4; mb += MB) { u32x4 gq[MB][2], oq[MB][2];
; #pragma unroll
;             for (int m = 0; m < MB; ++m)
; #pragma unroll
;                 for (int bj = 0; bj < 2; ++bj) { const size_t row = (size_t)(row0 + ai * HALF + (mb + m) * 16); const int col = col0 + bj * HALF;
;                     gq[m][bj] = *(const u32x4*)(gate + row * 4096 + goff + col); if (SECOND) oq[m][bj] = *(const u32x4*)(merged + row * 2048 + col); }
;             asm volatile("" ::: "memory");
; #pragma unroll
;             for (int m = 0; m < MB; ++m)
; #pragma unroll
;                 for (int bj = 0; bj < 2; ++bj) { const size_t row = (size_t)(row0 + ai * HALF + (mb + m) * 16); const int col = col0 + bj * HALF; const u32x4 g = gq[m][bj];
;                     f32x4 v0 = acc[ai][bj][mb + m][0], v1 = acc[ai][bj][mb + m][1];
;                     v0[0] *= bf_lo(g.x); v0[1] *= bf_hi(g.x); v0[2] *= bf_lo(g.y); v0[3] *= bf_hi(g.y);
;                     v1[0] *= bf_lo(g.z); v1[1] *= bf_hi(g.z); v1[2] *= bf_lo(g.w); v1[3] *= bf_hi(g.w);
;                     if (SECOND) { const u32x4 o = oq[m][bj];
;                         v0[0] += bf_lo(o.x); v0[1] += bf_hi(o.x); v0[2] += bf_lo(o.y); v0[3] += bf_hi(o.y);
;                         v1[0] += bf_lo(o.z); v1[1] += bf_hi(o.z); v1[2] += bf_lo(o.w); v1[3] += bf_hi(o.w); }
;                     *(u32x4*)(merged + row * 2048 + col) = PG8_PACK8(v0, v1); }
	v_lshlrev_b32_e32 v104, 16, v70
	v_and_b32_e32 v105, 0xffff0000, v70
	v_lshlrev_b32_e32 v66, 16, v67
	v_and_b32_e32 v67, 0xffff0000, v67
	v_lshlrev_b32_e32 v70, 16, v71
	v_and_b32_e32 v71, 0xffff0000, v71
	v_pk_fma_f32 v[64:65], v[64:65], v[66:67], v[70:71]
	v_lshlrev_b32_e32 v66, 16, v68
	v_and_b32_e32 v67, 0xffff0000, v68
	v_lshlrev_b32_e32 v70, 16, v72
	v_and_b32_e32 v71, 0xffff0000, v72
	v_pk_fma_f32 v[66:67], v[58:59], v[66:67], v[70:71]
	v_lshlrev_b32_e32 v58, 16, v69
	v_and_b32_e32 v59, 0xffff0000, v69
	v_lshlrev_b32_e32 v68, 16, v73
	v_and_b32_e32 v69, 0xffff0000, v73
	v_pk_fma_f32 v[62:63], v[62:63], v[102:103], v[104:105]
	v_pk_fma_f32 v[68:69], v[60:61], v[58:59], v[68:69]
	v_cvt_pk_bf16_f32 v58, v62, v63
	v_cvt_pk_bf16_f32 v59, v64, v65
	v_cvt_pk_bf16_f32 v60, v66, v67
	v_cvt_pk_bf16_f32 v61, v68, v69
	global_store_dwordx4 v[98:99], v[58:61], off
	s_waitcnt vmcnt(6)
	s_nop 0
	v_lshlrev_b32_e32 v58, 16, v74
	v_and_b32_e32 v59, 0xffff0000, v74
	s_waitcnt vmcnt(5)
	v_lshlrev_b32_e32 v60, 16, v78
	v_and_b32_e32 v61, 0xffff0000, v78
	v_pk_fma_f32 v[54:55], v[54:55], v[58:59], v[60:61]
	v_lshlrev_b32_e32 v58, 16, v75
	v_and_b32_e32 v59, 0xffff0000, v75
	v_lshlrev_b32_e32 v60, 16, v79
	v_and_b32_e32 v61, 0xffff0000, v79
	v_pk_fma_f32 v[56:57], v[56:57], v[58:59], v[60:61]
	v_lshlrev_b32_e32 v58, 16, v76
	v_and_b32_e32 v59, 0xffff0000, v76
	v_lshlrev_b32_e32 v60, 16, v80
	v_and_b32_e32 v61, 0xffff0000, v80
	v_pk_fma_f32 v[58:59], v[50:51], v[58:59], v[60:61]
	v_lshlrev_b32_e32 v50, 16, v77
	v_and_b32_e32 v51, 0xffff0000, v77
	v_lshlrev_b32_e32 v60, 16, v81
	v_and_b32_e32 v61, 0xffff0000, v81
	v_pk_fma_f32 v[60:61], v[52:53], v[50:51], v[60:61]
	v_cvt_pk_bf16_f32 v50, v54, v55
	v_cvt_pk_bf16_f32 v51, v56, v57
	v_cvt_pk_bf16_f32 v52, v58, v59
	v_cvt_pk_bf16_f32 v53, v60, v61
	global_store_dwordx4 v[98:99], v[50:53], off offset:256
	s_waitcnt vmcnt(5)
	s_nop 0
	v_lshlrev_b32_e32 v50, 16, v82
	v_and_b32_e32 v51, 0xffff0000, v82
	s_waitcnt vmcnt(4)
	v_lshlrev_b32_e32 v52, 16, v86
	v_and_b32_e32 v53, 0xffff0000, v86
	v_pk_fma_f32 v[46:47], v[46:47], v[50:51], v[52:53]
	v_lshlrev_b32_e32 v50, 16, v83
	v_and_b32_e32 v51, 0xffff0000, v83
	v_lshlrev_b32_e32 v52, 16, v87
	v_and_b32_e32 v53, 0xffff0000, v87
	v_pk_fma_f32 v[48:49], v[48:49], v[50:51], v[52:53]
	v_lshlrev_b32_e32 v50, 16, v84
	v_and_b32_e32 v51, 0xffff0000, v84
	v_lshlrev_b32_e32 v52, 16, v88
	v_and_b32_e32 v53, 0xffff0000, v88
	v_pk_fma_f32 v[50:51], v[42:43], v[50:51], v[52:53]
	v_lshlrev_b32_e32 v42, 16, v85
	v_and_b32_e32 v43, 0xffff0000, v85
	v_lshlrev_b32_e32 v52, 16, v89
	v_and_b32_e32 v53, 0xffff0000, v89
	v_pk_fma_f32 v[52:53], v[44:45], v[42:43], v[52:53]
	v_cvt_pk_bf16_f32 v42, v46, v47
	v_cvt_pk_bf16_f32 v43, v48, v49
	v_cvt_pk_bf16_f32 v44, v50, v51
	v_cvt_pk_bf16_f32 v45, v52, v53
	global_store_dwordx4 v[100:101], v[42:45], off
	v_add_u32_e32 v50, 0xb0, v156
	v_ashrrev_i32_e32 v51, 31, v50
	s_waitcnt vmcnt(4)
	v_lshlrev_b32_e32 v42, 16, v90
	v_and_b32_e32 v43, 0xffff0000, v90
	s_waitcnt vmcnt(3)
	v_lshlrev_b32_e32 v44, 16, v94
	v_and_b32_e32 v45, 0xffff0000, v94
	v_pk_fma_f32 v[38:39], v[38:39], v[42:43], v[44:45]
	v_lshlrev_b32_e32 v42, 16, v91
	v_and_b32_e32 v43, 0xffff0000, v91
	v_lshlrev_b32_e32 v44, 16, v95
	v_and_b32_e32 v45, 0xffff0000, v95
	v_pk_fma_f32 v[40:41], v[40:41], v[42:43], v[44:45]
	v_lshlrev_b32_e32 v42, 16, v92
	v_and_b32_e32 v43, 0xffff0000, v92
	v_lshlrev_b32_e32 v44, 16, v96
	v_and_b32_e32 v45, 0xffff0000, v96
	v_pk_fma_f32 v[42:43], v[34:35], v[42:43], v[44:45]
	v_lshlrev_b32_e32 v34, 16, v93
	v_and_b32_e32 v35, 0xffff0000, v93
	v_lshlrev_b32_e32 v44, 16, v97
	v_and_b32_e32 v45, 0xffff0000, v97
	v_pk_fma_f32 v[44:45], v[36:37], v[34:35], v[44:45]
	v_cvt_pk_bf16_f32 v34, v38, v39
	v_cvt_pk_bf16_f32 v35, v40, v41
	v_cvt_pk_bf16_f32 v36, v42, v43
	v_cvt_pk_bf16_f32 v37, v44, v45
	global_store_dwordx4 v[100:101], v[34:37], off offset:256
	v_lshlrev_b64 v[52:53], 13, v[50:51]
	v_lshl_add_u64 v[52:53], s[16:17], 0, v[52:53]
	v_add_u32_e32 v34, 0xa0, v156
	v_ashrrev_i32_e32 v35, 31, v34
	v_lshlrev_b64 v[36:37], 13, v[34:35]
	v_lshl_add_u64 v[36:37], s[16:17], 0, v[36:37]
	v_lshlrev_b64 v[34:35], 12, v[34:35]
	v_lshl_add_u64 v[42:43], v[36:37], 0, v[158:159]
	v_lshl_add_u64 v[38:39], s[10:11], 0, v[34:35]
	global_load_dwordx4 v[34:37], v[42:43], off nt
	v_lshl_add_u64 v[66:67], v[38:39], 0, v[158:159]
	global_load_dwordx4 v[38:41], v[66:67], off
	s_nop 0
	global_load_dwordx4 v[42:45], v[42:43], off offset:256 nt
	s_nop 0
	global_load_dwordx4 v[46:49], v[66:67], off offset:256
	v_lshlrev_b64 v[50:51], 12, v[50:51]
	v_lshl_add_u64 v[58:59], v[52:53], 0, v[158:159]
	v_lshl_add_u64 v[54:55], s[10:11], 0, v[50:51]
	global_load_dwordx4 v[50:53], v[58:59], off nt
	v_lshl_add_u64 v[68:69], v[54:55], 0, v[158:159]
	global_load_dwordx4 v[54:57], v[68:69], off
	s_nop 0
	global_load_dwordx4 v[58:61], v[58:59], off offset:256 nt
	s_nop 0
	global_load_dwordx4 v[62:65], v[68:69], off offset:256
	s_waitcnt vmcnt(7)
; __device__ __forceinline__ float bf_lo(unsigned w) { return __uint_as_float(w << 16); }
; __device__ __forceinline__ float bf_hi(unsigned w) { return __uint_as_float(w & 0xffff0000u); }
; #define PG8_PACK8(v0, v1) ((u32x4){cvt_pk_bf16((v0)[0], (v0)[1]), cvt_pk_bf16((v0)[2], (v0)[3]), cvt_pk_bf16((v1)[0], (v1)[1]), cvt_pk_bf16((v1)[2], (v1)[3])})
; #define PG8_BAR __builtin_amdgcn_s_barrier()
;     __device__ __forceinline__ void operator()(const f32x4 (&acc)[2][2][4][2], const Unit& u, int wr, int wc, int fr, int fq) const {
;     ...
;             for (int m = 0; m < MB; ++m)
; #pragma unroll
;                 for (int bj = 0; bj < 2; ++bj) { const size_t row = (size_t)(row0 + ai * HALF + (mb + m) * 16); const int col = col0 + bj * HALF; const u32x4 g = gq[m][bj];
;                     f32x4 v0 = acc[ai][bj][mb + m][0], v1 = acc[ai][bj][mb + m][1];
;                     v0[0] *= bf_lo(g.x); v0[1] *= bf_hi(g.x); v0[2] *= bf_lo(g.y); v0[3] *= bf_hi(g.y);
;                     v1[0] *= bf_lo(g.z); v1[1] *= bf_hi(g.z); v1[2] *= bf_lo(g.w); v1[3] *= bf_hi(g.w);
;                     if (SECOND) { const u32x4 o = oq[m][bj];
;                         v0[0] += bf_lo(o.x); v0[1] += bf_hi(o.x); v0[2] += bf_lo(o.y); v0[3] += bf_hi(o.y);
;                         v1[0] += bf_lo(o.z); v1[1] += bf_hi(o.z); v1[2] += bf_lo(o.w); v1[3] += bf_hi(o.w); }
;                     *(u32x4*)(merged + row * 2048 + col) = PG8_PACK8(v0, v1); }
;             asm volatile("" ::: "memory"); }
; template <class Prob, class Epi, class Sched>
; __device__ __forceinline__ void gemm_phase(PG8_LAS unsigned char* lds, const Prob g, const Sched& S, const Epi& E) {
;     ...
;         if (wr == 1) PG8_BAR;
	v_lshlrev_b32_e32 v70, 16, v34
	v_and_b32_e32 v71, 0xffff0000, v34
	s_waitcnt vmcnt(6)
	v_lshlrev_b32_e32 v72, 16, v38
	v_and_b32_e32 v73, 0xffff0000, v38
	v_lshlrev_b32_e32 v34, 16, v35
	v_and_b32_e32 v35, 0xffff0000, v35
	v_lshlrev_b32_e32 v38, 16, v39
	v_and_b32_e32 v39, 0xffff0000, v39
	v_pk_fma_f32 v[32:33], v[32:33], v[34:35], v[38:39]
	v_lshlrev_b32_e32 v34, 16, v36
	v_and_b32_e32 v35, 0xffff0000, v36
	v_lshlrev_b32_e32 v38, 16, v40
	v_and_b32_e32 v39, 0xffff0000, v40
	v_pk_fma_f32 v[34:35], v[26:27], v[34:35], v[38:39]
	v_lshlrev_b32_e32 v26, 16, v37
	v_and_b32_e32 v27, 0xffff0000, v37
	v_lshlrev_b32_e32 v36, 16, v41
	v_and_b32_e32 v37, 0xffff0000, v41
	v_pk_fma_f32 v[30:31], v[30:31], v[70:71], v[72:73]
	v_pk_fma_f32 v[36:37], v[28:29], v[26:27], v[36:37]
	v_cvt_pk_bf16_f32 v26, v30, v31
	v_cvt_pk_bf16_f32 v27, v32, v33
	v_cvt_pk_bf16_f32 v28, v34, v35
	v_cvt_pk_bf16_f32 v29, v36, v37
	global_store_dwordx4 v[66:67], v[26:29], off
	s_waitcnt vmcnt(6)
	s_nop 0
	v_lshlrev_b32_e32 v26, 16, v42
	v_and_b32_e32 v27, 0xffff0000, v42
	s_waitcnt vmcnt(5)
	v_lshlrev_b32_e32 v28, 16, v46
	v_and_b32_e32 v29, 0xffff0000, v46
	v_pk_fma_f32 v[22:23], v[22:23], v[26:27], v[28:29]
	v_lshlrev_b32_e32 v26, 16, v43
	v_and_b32_e32 v27, 0xffff0000, v43
	v_lshlrev_b32_e32 v28, 16, v47
	v_and_b32_e32 v29, 0xffff0000, v47
	v_pk_fma_f32 v[24:25], v[24:25], v[26:27], v[28:29]
	v_lshlrev_b32_e32 v26, 16, v44
	v_and_b32_e32 v27, 0xffff0000, v44
	v_lshlrev_b32_e32 v28, 16, v48
	v_and_b32_e32 v29, 0xffff0000, v48
	v_pk_fma_f32 v[26:27], v[18:19], v[26:27], v[28:29]
	v_lshlrev_b32_e32 v18, 16, v45
	v_and_b32_e32 v19, 0xffff0000, v45
	v_lshlrev_b32_e32 v28, 16, v49
	v_and_b32_e32 v29, 0xffff0000, v49
	v_pk_fma_f32 v[28:29], v[20:21], v[18:19], v[28:29]
	v_cvt_pk_bf16_f32 v18, v22, v23
	v_cvt_pk_bf16_f32 v19, v24, v25
	v_cvt_pk_bf16_f32 v20, v26, v27
	v_cvt_pk_bf16_f32 v21, v28, v29
	global_store_dwordx4 v[66:67], v[18:21], off offset:256
	s_waitcnt vmcnt(5)
	s_nop 0
	v_lshlrev_b32_e32 v18, 16, v50
	v_and_b32_e32 v19, 0xffff0000, v50
	s_waitcnt vmcnt(4)
	v_lshlrev_b32_e32 v20, 16, v54
	v_and_b32_e32 v21, 0xffff0000, v54
	v_pk_fma_f32 v[14:15], v[14:15], v[18:19], v[20:21]
	v_lshlrev_b32_e32 v18, 16, v51
	v_and_b32_e32 v19, 0xffff0000, v51
	v_lshlrev_b32_e32 v20, 16, v55
	v_and_b32_e32 v21, 0xffff0000, v55
	v_pk_fma_f32 v[16:17], v[16:17], v[18:19], v[20:21]
	v_lshlrev_b32_e32 v18, 16, v52
	v_and_b32_e32 v19, 0xffff0000, v52
	v_lshlrev_b32_e32 v20, 16, v56
	v_and_b32_e32 v21, 0xffff0000, v56
	v_pk_fma_f32 v[18:19], v[10:11], v[18:19], v[20:21]
	v_lshlrev_b32_e32 v10, 16, v53
	v_and_b32_e32 v11, 0xffff0000, v53
	v_lshlrev_b32_e32 v20, 16, v57
	v_and_b32_e32 v21, 0xffff0000, v57
	v_pk_fma_f32 v[20:21], v[12:13], v[10:11], v[20:21]
	v_cvt_pk_bf16_f32 v10, v14, v15
	v_cvt_pk_bf16_f32 v11, v16, v17
	v_cvt_pk_bf16_f32 v12, v18, v19
	v_cvt_pk_bf16_f32 v13, v20, v21
	global_store_dwordx4 v[68:69], v[10:13], off
	s_waitcnt vmcnt(4)
	s_nop 0
	v_lshlrev_b32_e32 v10, 16, v58
	v_and_b32_e32 v11, 0xffff0000, v58
	s_waitcnt vmcnt(3)
	v_lshlrev_b32_e32 v12, 16, v62
	v_and_b32_e32 v13, 0xffff0000, v62
	v_pk_fma_f32 v[6:7], v[6:7], v[10:11], v[12:13]
	v_lshlrev_b32_e32 v10, 16, v59
	v_and_b32_e32 v11, 0xffff0000, v59
	v_lshlrev_b32_e32 v12, 16, v63
	v_and_b32_e32 v13, 0xffff0000, v63
	v_pk_fma_f32 v[8:9], v[8:9], v[10:11], v[12:13]
	v_lshlrev_b32_e32 v10, 16, v60
	v_and_b32_e32 v11, 0xffff0000, v60
	v_lshlrev_b32_e32 v12, 16, v64
	v_and_b32_e32 v13, 0xffff0000, v64
	v_pk_fma_f32 v[10:11], v[2:3], v[10:11], v[12:13]
	v_lshlrev_b32_e32 v2, 16, v61
	v_and_b32_e32 v3, 0xffff0000, v61
	v_lshlrev_b32_e32 v12, 16, v65
	v_and_b32_e32 v13, 0xffff0000, v65
	v_pk_fma_f32 v[12:13], v[4:5], v[2:3], v[12:13]
	v_cvt_pk_bf16_f32 v2, v6, v7
	v_cvt_pk_bf16_f32 v3, v8, v9
	v_cvt_pk_bf16_f32 v4, v10, v11
	v_cvt_pk_bf16_f32 v5, v12, v13
	global_store_dwordx4 v[68:69], v[2:5], off offset:256
	s_cbranch_vccnz .LBB0_750
	s_andn2_b64 vcc, exec, s[12:13]
	s_cbranch_vccnz .LBB0_749
	s_barrier
	s_branch .LBB0_749
